# adds clamp-padded bias table in LDS for near-diagonal diff-attention tiles (32 immediate-offset ds_read_b32 instead of ~140 VALU index ops per tile) and one static s_setprio 1 for waves 4-7 during pro
# speedup vs baseline: 1.0387x; 1.0131x over previous
; #define LAS __attribute__((address_space(3)))
; template <int DQK, int DV, bool HAS_BIAS>
; __device__ __forceinline__ void attn_tile(AttnState<DQK, DV>& st, const LAS unsigned char* Kt, const LAS unsigned char* Vt, int bias_mode, const LAS float* tab, int rel0, int nkeys, bool first, LAS float* wsf, int lane) {
;     ...
;     if (HAS_BIAS && bias_mode == 2) {
;         asm volatile("" ::: "memory");
; #pragma unroll
;         for (int r = 0; r < 16; ++r) {
;             const int k = crow(r, hi);
; __device__ __forceinline__ void phase_attention(const Args& a, const Grp& G, LAS unsigned char* lds, const int tid_in) {
;     int tid_ = tid_in; asm volatile("" : "+v"(tid_));
;     const int tid = tid_, lane = tid & 63, wid = __builtin_amdgcn_readfirstlane(tid >> 6);
;     const float* tabg = (const float*)(a.ws + WS_TAB);
;     for (int i = tid; i < 8 * 192; i += 512) ((LAS float*)(lds + AL_TAB))[i] = tabg[i];
;     const float lam = tabg[1536];
;     const float* subln = a.in[13];
;     __syncthreads();
;     if (G.sample) {
;         if (wid < 4) {
;             constexpr int TBD = 64 * (64 * 2 + 16) + 64 * (128 * 2 + 64);
;             LAS unsigned char* wt = lds + AL_TILE + wid * TBD;
;             LAS float* wsf = (LAS float*)(lds + AL_WSF) + wid * 64;
;             const LAS float* tab0 = (const LAS float*)(lds + AL_TAB);
;             const unsigned char* cb = a.ws + WS_CACHE;
;             for (int wu = (int)blockIdx.x * 4 + wid; wu < 1024; wu += (int)gridDim.x * 4) {
;                 const int s = wu & 3; const int j0 = s == 0 ? 0 : 17 + 16 * (s - 1), j1 = 17 + 16 * s;
;                 if (wu < 512) {
;     ...
;  const int n = (wu >> 2) & 1, h = (wu >> 3) & 7, b = wu >> 6;
;                     attn_unit_wave<true>(G, cb, b, h, n, j0, j1, wu, (float*)(a.ws + WS_PO_D), (float*)(a.ws + WS_PM), (float*)(a.ws + WS_PL), wt, wsf, tab0, tid);
;     ...
;                 } else {
;     ...
;  const int i2 = wu - 512; const int h = (i2 >> 2) & 15, b = i2 >> 6;
;                     attn_unit_wave<false>(G, cb, b, h, 0, j0, j1, wu, (float*)(a.ws + WS_PO_M) - (size_t)512 * 32 * 64, (float*)(a.ws + WS_PM), (float*)(a.ws + WS_PL), wt, wsf, tab0, tid);
;     ...
;                 }
;             }
;         }
;     } else {
;         const int Gn = (int)gridDim.x, bx = (int)blockIdx.x;
;         const int vcu = (Gn % 8 == 0) ? (bx % 8) * (Gn / 8) + bx / 8 : bx;
.LBB0_510:
	s_or_b64 exec, exec, s[0:1]
	global_load_dword v192, v204, s[18:19] offset:2048
	s_cmp_eq_u32 s6, 0
	s_cselect_b64 s[0:1], -1, 0
	s_and_b64 s[2:3], s[0:1], exec
	s_mov_b32 s2, 0x2500000
	s_mov_b32 s3, 0x280000
	s_cselect_b32 s10, s2, 0x3a00000
	s_mov_b32 s2, 0x8000
	s_cselect_b32 s4, s3, 0x14000000
	s_mov_b32 s3, 0x300000
	s_cselect_b32 s13, 0x100, s2
	s_mov_b32 s2, 0x180000
	s_cselect_b32 s5, s3, 0x18000000
	s_mov_b32 s3, 0x500000
	s_mov_b32 s7, 0x540000
	s_cselect_b32 s2, s2, 0xc000000
	s_cselect_b32 s3, s3, 0x28000000
	s_cselect_b32 s7, s7, 0x2a000000
	s_add_u32 s14, s18, s10
	s_addc_u32 s15, s19, 0
	s_lshl_b32 s12, s13, 11
	s_add_u32 s16, s14, s12
	s_addc_u32 s17, s15, 0
	s_waitcnt vmcnt(0) lgkmcnt(0)
	v_writelane_b32 v246, s16, 0
	s_add_u32 s16, s16, s12
	v_writelane_b32 v246, s16, 1
	v_writelane_b32 v246, s17, 2
	s_addc_u32 s16, s17, 0
	v_writelane_b32 v246, s16, 3
	s_add_u32 s16, s14, s2
	s_addc_u32 s17, s15, 0
	v_writelane_b32 v246, s16, 4
	s_add_u32 s2, s14, s4
	s_barrier
	v_writelane_b32 v246, s17, 5
	v_writelane_b32 v246, s2, 6
	s_addc_u32 s2, s15, 0
	v_writelane_b32 v246, s2, 7
	s_add_u32 s2, s14, s5
	v_writelane_b32 v246, s2, 8
	s_addc_u32 s2, s15, 0
	v_writelane_b32 v246, s2, 9
	s_add_u32 s2, s14, s3
	s_addc_u32 s3, s15, 0
	v_writelane_b32 v246, s2, 10
	s_add_u32 s70, s14, s7
	s_addc_u32 s71, s15, 0
	v_writelane_b32 v246, s3, 11
	v_writelane_b32 v246, s14, 12
	s_cmp_lg_u32 s6, 0
	s_mov_b64 s[2:3], -1
	v_writelane_b32 v246, s15, 13
	s_cbranch_scc0 .LBB0_605
	v_readlane_b32 s2, v247, 11
	v_writelane_b32 v246, s20, 22
	v_readlane_b32 s3, v247, 12
	v_writelane_b32 v246, s18, 20
	s_andn2_b64 vcc, exec, s[2:3]
	s_nop 0
	v_writelane_b32 v246, s19, 21
	s_cbranch_vccnz .LBB0_604
	v_readlane_b32 s98, v247, 43
	s_cmp_lt_u32 s98, 4
	s_cbranch_scc1 .Lprio_skip
	s_setprio 1
.Lprio_skip:
	v_readlane_b32 s98, v247, 43
	v_mbcnt_lo_u32_b32 v224, -1, 0
	v_mbcnt_hi_u32_b32 v224, -1, v224
	s_mul_i32 s99, s98, 0x300
	s_mul_i32 s98, s98, 0x500
	s_add_i32 s98, s98, 0x11000
	v_add_u32_e32 v225, 0xffffffa0, v224
	v_max_i32_e32 v225, 0, v225
	v_min_i32_e32 v225, 0xbf, v225
	v_lshl_add_u32 v225, v225, 2, s99
	ds_read_b32 v226, v225
	v_add_u32_e32 v225, 0xffffffe0, v224
	v_max_i32_e32 v225, 0, v225
	v_min_i32_e32 v225, 0xbf, v225
	v_lshl_add_u32 v225, v225, 2, s99
	ds_read_b32 v227, v225
	v_add_u32_e32 v225, 32, v224
	v_max_i32_e32 v225, 0, v225
	v_min_i32_e32 v225, 0xbf, v225
	v_lshl_add_u32 v225, v225, 2, s99
	ds_read_b32 v228, v225
	v_add_u32_e32 v225, 0x60, v224
	v_max_i32_e32 v225, 0, v225
	v_min_i32_e32 v225, 0xbf, v225
	v_lshl_add_u32 v225, v225, 2, s99
	ds_read_b32 v229, v225
	v_add_u32_e32 v225, 0xa0, v224
	v_max_i32_e32 v225, 0, v225
	v_min_i32_e32 v225, 0xbf, v225
	v_lshl_add_u32 v225, v225, 2, s99
	ds_read_b32 v230, v225
	s_waitcnt lgkmcnt(0)
	v_lshl_add_u32 v225, v224, 2, s98
	ds_write_b32 v225, v226 offset:0
	ds_write_b32 v225, v227 offset:256
	ds_write_b32 v225, v228 offset:512
	ds_write_b32 v225, v229 offset:768
	ds_write_b32 v225, v230 offset:1024
	s_waitcnt lgkmcnt(0)
	s_barrier
	s_lshl_b32 s2, s13, 12
	v_readlane_b32 s3, v246, 1
	s_add_u32 s49, s3, s2
	v_readlane_b32 s3, v246, 3
	s_addc_u32 s50, s3, 0
	s_and_b64 s[0:1], s[0:1], exec
	s_mov_b32 s0, 0x480000
	s_cselect_b32 s0, s0, 0x24000000
	v_readlane_b32 s1, v246, 12
	s_add_u32 s51, s1, s0
	v_readlane_b32 s0, v246, 13
	s_addc_u32 s54, s0, 0
	s_add_u32 s0, s10, s2
	s_addc_u32 s1, 0, 0
	v_readlane_b32 s2, v246, 20
	v_readlane_b32 s3, v246, 21
	s_add_u32 s55, s2, s0
	s_addc_u32 s56, s3, s1
	s_add_u32 s0, s10, s12
	s_addc_u32 s1, 0, 0
	s_add_u32 s57, s2, s0
	s_addc_u32 s60, s3, s1
	s_add_u32 s61, s2, s7
	s_addc_u32 s74, s3, 0
	s_add_u32 s0, s2, s4
	v_writelane_b32 v246, s0, 14
	s_addc_u32 s0, s3, 0
	v_writelane_b32 v246, s0, 16
	s_add_u32 s0, s2, s5
	s_mov_b32 s11, s67
	v_mov_b32_e32 v193, v192
	v_writelane_b32 v246, s0, 18
	s_addc_u32 s0, s3, 0
	v_readlane_b32 s87, v247, 10
	v_writelane_b32 v246, s0, 19
	s_branch .LBB0_514

; template <bool DIFF>
; __device__ __forceinline__ void attn_unit_coop(const Grp& G, int b, int h, int qb, int n, LAS unsigned char* lds, const int tid_in) {
;     constexpr int DQK = DIFF ? 64 : 96, DV = DIFF ? 128 : 64, PK = DQK * 2 + 16, PV = DV * 2 + 64, KB = 64 * PK, VB = 64 * PV, TB = KB + VB, NDB = DV / 32;
;     int tid_ = tid_in; asm volatile("" : "+v"(tid_));
;     const int tid = tid_, lane = tid & 63, wid = __builtin_amdgcn_readfirstlane(tid >> 6), q = lane & 31, hi = lane >> 5;
;     const size_t seq0 = (size_t)b * TS;
;     const int qrow0 = qb * 256 + wid * 32;
;     const int NT = 4 * qb + 4, my_nt = 4 * qb + (wid >> 1) + 1;
;     const LAS float* tab = (const LAS float*)(lds + AL_TAB) + h * 192;
;     LAS float* wsf = (LAS float*)(lds + AL_WSF) + wid * 64;
;     LAS unsigned char* tiles = lds + AL_TILE;
;     {
;         AttnState<DQK, DV> st; attn_init(st);
;         if (DIFF) { const bf16* qp = G.QD + (seq0 + qrow0 + q) * 1024 + h * 128 + n * 64 + hi * 8;
; #pragma unroll
;             for (int ks = 0; ks < 4; ++ks) st.qf[ks] = *(const bf16x8*)(qp + ks * 16);
;         } else { const bf16* qn = G.QN + (seq0 + qrow0 + q) * 1024 + h * 64 + hi * 8; const bf16* qr = G.QR + (seq0 + qrow0 + q) * 512 + h * 32 + hi * 8;
; #pragma unroll
;             for (int ks = 0; ks < 4; ++ks) st.qf[ks] = *(const bf16x8*)(qn + ks * 16);
; #pragma unroll
;             for (int ks = 0; ks < 2; ++ks) st.qf[4 + ks] = *(const bf16x8*)(qr + ks * 16);
;         }
;         const bf16* ksrc = (DIFF ? G.KD + h * 128 + n * 64 : G.KN + h * 64) + (seq0 + (tid >> 3)) * 1024 + (tid & 7) * 8;
;         const int kdst = (tid >> 3) * PK + (tid & 7) * 16;
;         const bf16* k2src = G.KR + (seq0 + ((tid & 255) >> 2)) * 32 + (tid & 3) * 8;
;         const int k2dst = ((tid & 255) >> 2) * PK + 128 + (tid & 3) * 16;
;         const bf16* vsrc = DIFF ? G.VD + (seq0 + (tid >> 4)) * 1024 + h * 128 + (tid & 15) * 8 : G.VM + (seq0 + (tid >> 3)) * 1024 + h * 64 + (tid & 7) * 8;
;         const int vdst = DIFF ? KB + (tid >> 4) * PV + (tid & 15) * 16 : KB + (tid >> 3) * PV + (tid & 7) * 16;
;         u32x4 rkA, rk2A = {0u, 0u, 0u, 0u}, rv0A, rv1A = {0u, 0u, 0u, 0u}, rkB = {0u, 0u, 0u, 0u}, rk2B = {0u, 0u, 0u, 0u}, rv0B = {0u, 0u, 0u, 0u}, rv1B = {0u, 0u, 0u, 0u};
;     ...
;         ATT_LOAD(A, 0); ATT_STORE(A, tiles);
;         __syncthreads();
;         ATT_LOAD(A, 1);
.LBB0_519:
	v_mov_b32_e32 v28, v212
	v_mov_b32_e32 v15, v185
	v_ashrrev_i32_e32 v12, 3, v28
	v_ashrrev_i32_e32 v13, 31, v12
	v_lshl_add_u64 v[0:1], s[24:25], 0, v[12:13]
	v_lshlrev_b64 v[0:1], 11, v[0:1]
	v_lshlrev_b32_e32 v2, 4, v28
	v_ashrrev_i32_e32 v18, 4, v28
	v_lshl_add_u64 v[0:1], s[30:31], 0, v[0:1]
	v_and_b32_e32 v14, 0x70, v2
	v_ashrrev_i32_e32 v19, 31, v18
	v_lshl_add_u64 v[16:17], v[0:1], 0, v[14:15]
	v_lshl_add_u64 v[0:1], s[24:25], 0, v[18:19]
	v_lshlrev_b64 v[0:1], 11, v[0:1]
	v_lshl_add_u64 v[0:1], s[14:15], 0, v[0:1]
	v_and_b32_e32 v20, 0xf0, v2
	v_mov_b32_e32 v21, v185
	v_lshl_add_u64 v[22:23], v[0:1], 0, v[20:21]
	global_load_dwordx4 v[0:3], v[16:17], off
	global_load_dwordx4 v[4:7], v[22:23], off
	v_add_co_u32_e32 v8, vcc, s53, v22
	s_xor_b64 s[36:37], s[0:1], -1
	s_nop 0
	v_addc_co_u32_e32 v9, vcc, 0, v23, vcc
	global_load_dwordx4 v[8:11], v[8:9], off
	s_and_b64 s[0:1], s[0:1], exec
	s_cselect_b32 s0, s48, s90
	v_readfirstlane_b32 s1, v28
	s_lshl_b32 s2, s0, 8
	s_ashr_i32 s3, s1, 1
	s_lshl_b32 s7, s0, 2
	s_ashr_i32 s40, s1, 7
	s_and_b32 s41, s1, 0x3fffffc0
	v_mad_u64_u32 v[24:25], s[0:1], v12, s76, v[14:15]
	s_andn2_b32 s3, s3, 31
	s_movk_i32 s0, 0x140
	v_mad_u64_u32 v[26:27], s[0:1], v18, s0, v[20:21]
	s_add_i32 s42, s3, s2
	s_ashr_i32 s0, s42, 31
	s_add_u32 s38, s24, s42
	v_and_b32_e32 v194, 31, v28
	s_addc_u32 s39, s25, s0
	v_add_u32_e32 v214, 0, v24
	v_or_b32_e32 v24, s38, v194
	v_add_co_u32_e32 v16, vcc, s62, v16
	v_mov_b32_e32 v25, s39
	v_bfe_u32 v191, v28, 5, 1
	v_addc_co_u32_e32 v17, vcc, 0, v17, vcc
	v_lshlrev_b64 v[24:25], 11, v[24:25]
	v_lshlrev_b32_e32 v184, 4, v191
	v_add_u32_e32 v215, 0, v26
	v_add_co_u32_e32 v26, vcc, s62, v22
	v_lshl_add_u64 v[24:25], s[28:29], 0, v[24:25]
	s_nop 0
	v_addc_co_u32_e32 v27, vcc, 0, v23, vcc
	s_mov_b32 s0, 0x30000
	v_lshl_add_u64 v[24:25], v[24:25], 0, v[184:185]
	v_add_co_u32_e32 v22, vcc, s0, v22
	global_load_dwordx4 v[112:115], v[24:25], off
	global_load_dwordx4 v[116:119], v[24:25], off offset:32
	global_load_dwordx4 v[120:123], v[24:25], off offset:64
	global_load_dwordx4 v[124:127], v[24:25], off offset:96
	v_addc_co_u32_e32 v23, vcc, 0, v23, vcc
	s_lshl_b32 s0, s41, 2
	s_add_i32 s6, s7, 4
	s_add_i32 s7, s40, s7
	s_add_i32 s40, s0, 0
	v_mov_b32_e32 v142, v185
	v_mov_b32_e32 v143, v185
	v_mov_b32_e32 v48, v185
	v_mov_b32_e32 v49, v185
	v_mov_b32_e32 v62, v185
	v_mov_b32_e32 v63, v185
	v_mov_b32_e32 v140, v185
	v_mov_b32_e32 v141, v185
	v_mov_b32_e32 v50, v185
	v_mov_b32_e32 v51, v185
	v_mov_b32_e32 v52, v185
	v_mov_b32_e32 v53, v185
	v_mov_b32_e32 v54, v185
	v_mov_b32_e32 v55, v185
	v_mov_b32_e32 v56, v185
	v_mov_b32_e32 v57, v185
	v_mov_b32_e32 v58, v185
	v_mov_b32_e32 v59, v185
	s_waitcnt vmcnt(6)
	ds_write_b128 v214, v[0:3] offset:8192
	s_waitcnt vmcnt(5)
	ds_write_b128 v215, v[4:7] offset:17408
	s_waitcnt vmcnt(4)
	ds_write_b128 v215, v[8:11] offset:27648
	s_waitcnt lgkmcnt(0)
	s_barrier
	global_load_dwordx4 v[128:131], v[16:17], off
	global_load_dwordx4 v[132:135], v[26:27], off
	global_load_dwordx4 v[136:139], v[22:23], off
	v_and_b32_e32 v0, 63, v28
	v_lshlrev_b32_e32 v1, 2, v191
	v_lshrrev_b32_e32 v3, 2, v28
	v_and_b32_e32 v4, 16, v28
	v_lshlrev_b32_e32 v5, 2, v28
	v_and_or_b32 v4, v5, 12, v4
	v_cmp_gt_u32_e64 s[0:1], 32, v0
	v_and_or_b32 v0, v3, 3, v1
	v_lshlrev_b32_e32 v4, 1, v4
	v_mul_u32_u24_e32 v0, 0x140, v0
	v_add3_u32 v217, 0, v4, v0
	v_or_b32_e32 v0, s42, v194
	v_sub_u32_e32 v218, v1, v0
	v_sub_u32_e32 v0, v1, v194
	v_subrev_u32_e32 v0, s3, v0
	v_subrev_u32_e32 v219, s2, v0
	s_mul_i32 s98, s85, 5
	s_add_i32 s98, s98, 0x11380
	v_lshl_add_u32 v225, v218, 2, s98
	v_lshlrev_b64 v[0:1], 11, v[18:19]
	v_or_b32_e32 v0, v0, v20
	v_lshl_add_u64 v[196:197], s[22:23], 0, v[0:1]
	v_lshlrev_b64 v[0:1], 11, v[12:13]
	v_mad_u32_u24 v2, v194, s76, 0
	v_or_b32_e32 v0, v0, v14
	v_lshl_add_u64 v[198:199], s[34:35], 0, v[0:1]
	v_mov_b32_e32 v60, v185
	v_mov_b32_e32 v61, v185
	v_add_u32_e32 v221, v2, v184
	v_mov_b64_e32 v[32:33], v[48:49]
	v_mov_b64_e32 v[16:17], v[48:49]
	v_mov_b64_e32 v[0:1], v[48:49]
	v_mov_b64_e32 v[78:79], v[62:63]
	v_mov_b64_e32 v[146:147], v[142:143]
	v_mov_b64_e32 v[150:151], v[142:143]
	s_mov_b32 s58, 0
	v_lshl_add_u32 v216, v194, 2, s40
	v_add_u32_e32 v213, s40, v184
	s_sub_i32 s92, 0, s42
	v_mov_b32_e32 v220, 0
	v_mov_b64_e32 v[34:35], v[50:51]
	v_mov_b64_e32 v[36:37], v[52:53]
	v_mov_b64_e32 v[38:39], v[54:55]
	v_mov_b64_e32 v[40:41], v[56:57]
	v_mov_b64_e32 v[42:43], v[58:59]
	v_mov_b64_e32 v[44:45], v[60:61]
	v_mov_b64_e32 v[46:47], v[62:63]
	v_mov_b64_e32 v[18:19], v[50:51]
	v_mov_b64_e32 v[20:21], v[52:53]
	v_mov_b64_e32 v[22:23], v[54:55]
	v_mov_b64_e32 v[24:25], v[56:57]
	v_mov_b64_e32 v[26:27], v[58:59]
	v_mov_b64_e32 v[28:29], v[60:61]
	v_mov_b64_e32 v[30:31], v[62:63]
	v_mov_b64_e32 v[2:3], v[50:51]
	v_mov_b64_e32 v[4:5], v[52:53]
	v_mov_b64_e32 v[6:7], v[54:55]
	v_mov_b64_e32 v[8:9], v[56:57]
	v_mov_b64_e32 v[10:11], v[58:59]
	v_mov_b64_e32 v[12:13], v[60:61]
	v_mov_b64_e32 v[14:15], v[62:63]
	v_mov_b64_e32 v[76:77], v[60:61]
	v_mov_b64_e32 v[74:75], v[58:59]
	v_mov_b64_e32 v[72:73], v[56:57]
	v_mov_b64_e32 v[70:71], v[54:55]
	v_mov_b64_e32 v[68:69], v[52:53]
	v_mov_b64_e32 v[66:67], v[50:51]
	v_mov_b64_e32 v[64:65], v[48:49]
	v_mov_b32_e32 v184, 0
	v_mov_b64_e32 v[144:145], v[140:141]
	v_mov_b64_e32 v[148:149], v[140:141]
	s_mov_b32 s59, 0

; __device__ __forceinline__ int crow(int r, int hi) { return (r & 3) + 8 * (r >> 2) + 4 * hi; }
; template <int DQK, int DV, bool HAS_BIAS>
; __device__ __forceinline__ void attn_tile(AttnState<DQK, DV>& st, const LAS unsigned char* Kt, const LAS unsigned char* Vt, int bias_mode, const LAS float* tab, int rel0, int nkeys, bool first, LAS float* wsf, int lane) {
;     ...
;     if (HAS_BIAS && bias_mode == 2) {
;         asm volatile("" ::: "memory");
; #pragma unroll
;         for (int r = 0; r < 16; ++r) {
;             const int k = crow(r, hi);
;             const int i0 = min(max(rel0 + k + 128, 0), 191), i1 = min(max(rel0 + k + 160, 0), 191);
;             p0[r] = tab[i0] + st.negm[r]; p1[r] = tab[i1] + st.negm[r];
;         }
;         p0 = __builtin_amdgcn_mfma_f32_32x32x16_bf16(ka[0], st.qf[0], p0, 0, 0, 0);
;         p1 = __builtin_amdgcn_mfma_f32_32x32x16_bf16(kb[0], st.qf[0], p1, 0, 0, 0);
.LBB0_525:
	s_andn2_b64 vcc, exec, s[2:3]
	s_cbranch_vccnz .LBB0_527
	s_nop 6
	v_lshl_add_u32 v224, s58, 2, v225
	ds_read_b32 v80, v224 offset:0
	ds_read_b32 v96, v224 offset:128
	ds_read_b32 v81, v224 offset:4
	ds_read_b32 v97, v224 offset:132
	ds_read_b32 v82, v224 offset:8
	ds_read_b32 v98, v224 offset:136
	ds_read_b32 v83, v224 offset:12
	ds_read_b32 v99, v224 offset:140
	ds_read_b32 v84, v224 offset:32
	ds_read_b32 v100, v224 offset:160
	ds_read_b32 v85, v224 offset:36
	ds_read_b32 v101, v224 offset:164
	ds_read_b32 v86, v224 offset:40
	ds_read_b32 v102, v224 offset:168
	ds_read_b32 v87, v224 offset:44
	ds_read_b32 v103, v224 offset:172
	ds_read_b32 v88, v224 offset:64
	ds_read_b32 v104, v224 offset:192
	ds_read_b32 v89, v224 offset:68
	ds_read_b32 v105, v224 offset:196
	ds_read_b32 v90, v224 offset:72
	ds_read_b32 v106, v224 offset:200
	ds_read_b32 v91, v224 offset:76
	ds_read_b32 v107, v224 offset:204
	ds_read_b32 v92, v224 offset:96
	ds_read_b32 v108, v224 offset:224
	ds_read_b32 v93, v224 offset:100
	ds_read_b32 v109, v224 offset:228
	ds_read_b32 v94, v224 offset:104
	ds_read_b32 v110, v224 offset:232
	ds_read_b32 v95, v224 offset:108
	ds_read_b32 v111, v224 offset:236
	s_waitcnt lgkmcnt(0)
	v_pk_add_f32 v[94:95], v[78:79], v[94:95]
	s_waitcnt lgkmcnt(3)
	v_pk_add_f32 v[92:93], v[76:77], v[92:93]
	v_pk_add_f32 v[90:91], v[74:75], v[90:91]
	v_pk_add_f32 v[88:89], v[72:73], v[88:89]
	v_pk_add_f32 v[86:87], v[70:71], v[86:87]
	v_pk_add_f32 v[84:85], v[68:69], v[84:85]
	v_pk_add_f32 v[82:83], v[66:67], v[82:83]
	v_pk_add_f32 v[80:81], v[64:65], v[80:81]
	s_waitcnt lgkmcnt(1)
	v_pk_add_f32 v[110:111], v[78:79], v[110:111]
	s_waitcnt lgkmcnt(0)
	v_pk_add_f32 v[108:109], v[76:77], v[108:109]
	v_pk_add_f32 v[106:107], v[74:75], v[106:107]
	v_pk_add_f32 v[104:105], v[72:73], v[104:105]
	v_pk_add_f32 v[102:103], v[70:71], v[102:103]
	v_pk_add_f32 v[100:101], v[68:69], v[100:101]
	v_pk_add_f32 v[98:99], v[66:67], v[98:99]
	v_pk_add_f32 v[96:97], v[64:65], v[96:97]
	s_waitcnt vmcnt(6)
	v_mfma_f32_32x32x16_bf16 v[80:95], v[180:183], v[112:115], v[80:95]
	v_mfma_f32_32x32x16_bf16 v[96:111], v[176:179], v[112:115], v[96:111]

; __device__ __forceinline__ int crow(int r, int hi) { return (r & 3) + 8 * (r >> 2) + 4 * hi; }
; template <int DQK, int DV, bool HAS_BIAS>
; __device__ __forceinline__ void attn_tile(AttnState<DQK, DV>& st, const LAS unsigned char* Kt, const LAS unsigned char* Vt, int bias_mode, const LAS float* tab, int rel0, int nkeys, bool first, LAS float* wsf, int lane) {
;     ...
;     if (HAS_BIAS && bias_mode == 2) {
;         asm volatile("" ::: "memory");
; #pragma unroll
;         for (int r = 0; r < 16; ++r) {
;             const int k = crow(r, hi);
;             const int i0 = min(max(rel0 + k + 128, 0), 191), i1 = min(max(rel0 + k + 160, 0), 191);
;             p0[r] = tab[i0] + st.negm[r]; p1[r] = tab[i1] + st.negm[r];
;         }
;         p0 = __builtin_amdgcn_mfma_f32_32x32x16_bf16(ka[0], st.qf[0], p0, 0, 0, 0);
;         p1 = __builtin_amdgcn_mfma_f32_32x32x16_bf16(kb[0], st.qf[0], p1, 0, 0, 0);
.LBB0_545:
	s_andn2_b64 vcc, exec, s[2:3]
	s_cbranch_vccnz .LBB0_547
	s_nop 6
	v_lshl_add_u32 v224, s58, 2, v225
	ds_read_b32 v80, v224 offset:256
	ds_read_b32 v96, v224 offset:384
	ds_read_b32 v81, v224 offset:260
	ds_read_b32 v97, v224 offset:388
	ds_read_b32 v82, v224 offset:264
	ds_read_b32 v98, v224 offset:392
	ds_read_b32 v83, v224 offset:268
	ds_read_b32 v99, v224 offset:396
	ds_read_b32 v84, v224 offset:288
	ds_read_b32 v100, v224 offset:416
	ds_read_b32 v85, v224 offset:292
	ds_read_b32 v101, v224 offset:420
	ds_read_b32 v86, v224 offset:296
	ds_read_b32 v102, v224 offset:424
	ds_read_b32 v87, v224 offset:300
	ds_read_b32 v103, v224 offset:428
	ds_read_b32 v88, v224 offset:320
	ds_read_b32 v104, v224 offset:448
	ds_read_b32 v89, v224 offset:324
	ds_read_b32 v105, v224 offset:452
	ds_read_b32 v90, v224 offset:328
	ds_read_b32 v106, v224 offset:456
	ds_read_b32 v91, v224 offset:332
	ds_read_b32 v107, v224 offset:460
	ds_read_b32 v92, v224 offset:352
	ds_read_b32 v108, v224 offset:480
	ds_read_b32 v93, v224 offset:356
	ds_read_b32 v109, v224 offset:484
	ds_read_b32 v94, v224 offset:360
	ds_read_b32 v110, v224 offset:488
	ds_read_b32 v95, v224 offset:364
	ds_read_b32 v111, v224 offset:492
	s_waitcnt lgkmcnt(0)
	v_pk_add_f32 v[94:95], v[78:79], v[94:95]
	s_waitcnt lgkmcnt(3)
	v_pk_add_f32 v[92:93], v[76:77], v[92:93]
	v_pk_add_f32 v[90:91], v[74:75], v[90:91]
	v_pk_add_f32 v[88:89], v[72:73], v[88:89]
	v_pk_add_f32 v[86:87], v[70:71], v[86:87]
	v_pk_add_f32 v[84:85], v[68:69], v[84:85]
	v_pk_add_f32 v[82:83], v[66:67], v[82:83]
	v_pk_add_f32 v[80:81], v[64:65], v[80:81]
	s_waitcnt lgkmcnt(1)
	v_pk_add_f32 v[110:111], v[78:79], v[110:111]
	s_waitcnt lgkmcnt(0)
	v_pk_add_f32 v[108:109], v[76:77], v[108:109]
	v_pk_add_f32 v[106:107], v[74:75], v[106:107]
	v_pk_add_f32 v[104:105], v[72:73], v[104:105]
	v_pk_add_f32 v[102:103], v[70:71], v[102:103]
	v_pk_add_f32 v[100:101], v[68:69], v[100:101]
	v_pk_add_f32 v[98:99], v[66:67], v[98:99]
	v_pk_add_f32 v[96:97], v[64:65], v[96:97]
	v_mfma_f32_32x32x16_bf16 v[80:95], v[180:183], v[112:115], v[80:95]
	s_nop 0
	v_mfma_f32_32x32x16_bf16 v[96:111], v[176:179], v[112:115], v[96:111]

; __device__ __forceinline__ void phase_attention(const Args& a, const Grp& G, LAS unsigned char* lds, const int tid_in) {
;     ...
;         const int Gn = (int)gridDim.x, bx = (int)blockIdx.x;
;         const int vcu = (Gn % 8 == 0) ? (bx % 8) * (Gn / 8) + bx / 8 : bx;
;         for (int v = vcu; v < 256; v += Gn) {
;             const int p = v & 3;
;     ...
;             for (int r = 0; r < GBATCH * 8 / 64; ++r) { const int bh = r * 64 + (v >> 2), b = bh >> 3, h = bh & 7;
;                 for (int n = 0; n < 2; ++n)
;                     for (int i = 0; i < 2; ++i) attn_unit_coop<true>(G, b, h, i ? p : 7 - p, n, lds, tid_in);
;                 asm volatile("s_waitcnt vmcnt(0)" ::: "memory"); __syncthreads();
;                 int t2 = tid_in; asm volatile("" : "+v"(t2));
;                 diffmix_block(G, b, h, 7 - p, lam, subln, t2); diffmix_block(G, b, h, p, lam, subln, t2); }
;     ...
;             for (int r = 0; r < GBATCH * 16 / 64; ++r) { const int bh = r * 64 + (v >> 2), b = bh >> 4, h = bh & 15;
;                 for (int i = 0; i < 2; ++i) attn_unit_coop<false>(G, b, h, i ? p : 7 - p, 0, lds, tid_in); }
;     ...
;         }
.LBB0_604:
	s_setprio 0
	v_readlane_b32 s82, v247, 39
	v_readlane_b32 s90, v247, 41
	v_readlane_b32 s74, v247, 44
	v_readlane_b32 s24, v247, 47
	v_readlane_b32 s22, v247, 51
	v_readlane_b32 s50, v247, 53
	v_readlane_b32 s18, v246, 20
	s_mov_b64 s[2:3], 0
	v_readlane_b32 s80, v247, 35
	v_readlane_b32 s81, v247, 38
	v_readlane_b32 s83, v247, 40
	v_readlane_b32 s91, v247, 42
	v_readlane_b32 s84, v247, 43
	v_readlane_b32 s75, v247, 45
	v_readlane_b32 s85, v247, 46
	v_readlane_b32 s25, v247, 48
	v_readlane_b32 s42, v247, 49
	v_readlane_b32 s61, v247, 50
	v_readlane_b32 s23, v247, 52
	v_readlane_b32 s51, v247, 54
	v_readlane_b32 s19, v246, 21
	v_readlane_b32 s20, v246, 22
